# gla_a LDS-staged loads (now waits for the band loop's trailing prefetch before reusing its registers) + sample-row small GEMM loads up front + bias table loads batched
# speedup vs baseline: 1.0036x; 1.0036x over previous
.LBB0_699:
	s_add_i32 s38, s21, s95
	v_readlane_b32 s50, v244, 38
	s_cmpk_gt_i32 s38, 0x7ff
	v_readlane_b32 s51, v244, 39
	s_barrier
	s_cbranch_scc1 .LBB0_704
	s_mulk_i32 s21, 0x4400
	s_add_i32 s10, s21, 0
	s_add_u32 s42, s0, 0x1cc00000
	s_addc_u32 s43, s1, 0
	s_add_u32 s44, s0, 0x1ec80000
	v_mov_b32_e32 v65, 0
	v_lshlrev_b32_e32 v64, 2, v162
	s_addc_u32 s45, s1, 0
	v_lshl_add_u64 v[0:1], s[0:1], 0, v[64:65]
	s_mov_b64 s[8:9], 0xf800000
	s_add_u32 s21, s0, 0x3600000
	v_lshl_add_u64 v[68:69], v[0:1], 0, s[8:9]
	s_addc_u32 s33, s1, 0
	s_lshr_b32 s8, s20, 6
	v_lshlrev_b32_e32 v3, 15, v224
	s_mov_b32 s9, 0x18b00040
	s_ashr_i32 s39, s38, 31
	v_mul_u32_u24_e32 v0, 0x90, v162
	v_add_u32_e32 v1, s10, v225
	v_add_u32_e32 v2, s10, v226
	v_or3_b32 v64, v3, v163, s9
	s_add_i32 s20, s95, s8
	s_lshl_b64 s[8:9], s[38:39], 15
	v_lshlrev_b32_e32 v3, 10, v222
	s_ashr_i32 s93, s92, 31
	s_mov_b32 s41, 0
	v_lshlrev_b32_e32 v66, 14, v162
	v_or3_b32 v70, s8, v3, v223
	v_mov_b32_e32 v71, s9
	s_lshl_b64 s[46:47], s[92:93], 15
	v_lshlrev_b32_e32 v72, 2, v162
	v_mov_b32_e32 v73, v65
	v_add_u32_e32 v67, s10, v0
	v_add_u32_e32 v78, v1, v163
	v_add_u32_e32 v79, v2, v163
	s_waitcnt vmcnt(0)
	v_lshrrev_b32_e32 v214, 3, v162
	v_and_b32_e32 v215, 7, v162
	v_lshlrev_b32_e32 v142, 15, v214
	v_lshl_or_b32 v142, v215, 4, v142
	v_mul_u32_u24_e32 v160, 0x90, v214
	v_lshl_add_u32 v160, v215, 4, v160
	v_add_u32_e32 v160, s10, v160
	v_lshrrev_b32_e32 v214, 4, v162
	v_and_b32_e32 v215, 15, v162
	v_lshlrev_b32_e32 v143, 16, v214
	v_lshl_or_b32 v143, v215, 4, v143
	v_mul_u32_u24_e32 v161, 0x110, v214
	v_lshl_add_u32 v161, v215, 4, v161
	v_add_u32_e32 v161, s10, v161
	v_mul_u32_u24_e32 v164, 0x110, v162
	v_add_u32_e32 v164, s10, v164
	v_and_b32_e32 v214, 31, v162
	v_lshrrev_b32_e32 v215, 5, v162
	v_mul_u32_u24_e32 v165, 0x90, v214
	v_lshl_add_u32 v165, v215, 4, v165
	v_add_u32_e32 v165, s10, v165
	v_add_u32_e32 v165, 0x2400, v165

.LBB0_933:
	s_and_b32 s0, s9, 0xffffffc0
	v_or_b32_e32 v0, s0, v40
	v_ashrrev_i32_e32 v1, 31, v0
	v_lshlrev_b64 v[0:1], 11, v[0:1]
	s_waitcnt vmcnt(0)
	v_lshl_add_u64 v[90:91], v[34:35], 0, v[0:1]
	v_add_co_u32_e32 v94, vcc, 0x8000, v90
	s_and_b32 s15, s8, 0x3e0
	s_nop 0
	v_addc_co_u32_e32 v95, vcc, 0, v91, vcc
	v_add_co_u32_e32 v96, vcc, s20, v90
	v_or_b32_e32 v0, s15, v40
	s_nop 0
	v_addc_co_u32_e32 v97, vcc, 0, v91, vcc
	v_lshlrev_b32_e32 v32, 11, v0
	v_add_co_u32_e32 v98, vcc, 0x18000, v90
	v_lshl_add_u64 v[92:93], v[36:37], 0, v[32:33]
	s_nop 0
	v_addc_co_u32_e32 v99, vcc, 0, v91, vcc
	v_add_co_u32_e32 v100, vcc, 0x8000, v92
	global_load_dwordx4 v[0:3], v[90:91], off
	global_load_dwordx4 v[4:7], v[94:95], off
	v_addc_co_u32_e32 v101, vcc, 0, v93, vcc
	global_load_dwordx4 v[8:11], v[96:97], off
	global_load_dwordx4 v[12:15], v[98:99], off
	global_load_dwordx4 v[16:19], v[100:101], off
	global_load_dwordx4 v[20:23], v[92:93], off
	global_load_dwordx4 v[54:57], v[90:91], off offset:64
	global_load_dwordx4 v[58:61], v[94:95], off offset:64
	global_load_dwordx4 v[62:65], v[96:97], off offset:64
	global_load_dwordx4 v[66:69], v[98:99], off offset:64
	global_load_dwordx4 v[70:73], v[92:93], off offset:64
	global_load_dwordx4 v[74:77], v[100:101], off offset:64
	global_load_dwordx4 v[102:105], v[90:91], off offset:128
	global_load_dwordx4 v[106:109], v[94:95], off offset:128
	global_load_dwordx4 v[110:113], v[96:97], off offset:128
	global_load_dwordx4 v[114:117], v[98:99], off offset:128
	global_load_dwordx4 v[118:121], v[92:93], off offset:128
	global_load_dwordx4 v[122:125], v[100:101], off offset:128
	global_load_dwordx4 v[126:129], v[90:91], off offset:192
	global_load_dwordx4 v[130:133], v[94:95], off offset:192
	global_load_dwordx4 v[134:137], v[96:97], off offset:192
	global_load_dwordx4 v[138:141], v[98:99], off offset:192
	global_load_dwordx4 v[142:145], v[92:93], off offset:192
	global_load_dwordx4 v[146:149], v[100:101], off offset:192
	s_add_i32 s11, s11, s96
	s_add_i32 s8, s8, s86
	s_add_i32 s9, s9, s10
	s_waitcnt vmcnt(23)
	ds_write_b128 v46, v[0:3]
	s_waitcnt vmcnt(22)
	ds_write_b128 v46, v[4:7] offset:1280
	s_waitcnt vmcnt(21)
	ds_write_b128 v46, v[8:11] offset:2560
	s_waitcnt vmcnt(20)
	ds_write_b128 v46, v[12:15] offset:3840
	s_waitcnt vmcnt(18)
	ds_write_b128 v46, v[20:23] offset:5120
	ds_write_b128 v46, v[16:19] offset:6400
	ds_read_b128 v[16:19], v47 offset:5120
	ds_read_b128 v[0:3], v47
	ds_read_b128 v[78:81], v47 offset:32
	s_waitcnt lgkmcnt(1)
	v_mfma_f32_32x32x16_bf16 v[0:15], v[0:3], v[16:19], 0
	ds_read_b128 v[82:85], v47 offset:5152
	ds_read_b128 v[20:23], v47 offset:2560
	s_waitcnt lgkmcnt(1)
	v_mfma_f32_32x32x16_bf16 v[0:15], v[78:81], v[82:85], v[0:15]
	ds_read_b128 v[78:81], v47 offset:2592
	s_waitcnt vmcnt(17)
	ds_write_b128 v46, v[54:57]
	s_waitcnt vmcnt(16)
	ds_write_b128 v46, v[58:61] offset:1280
	s_waitcnt vmcnt(15)
	ds_write_b128 v46, v[62:65] offset:2560
	s_waitcnt vmcnt(14)
	ds_write_b128 v46, v[66:69] offset:3840
	s_waitcnt vmcnt(13)
	ds_write_b128 v46, v[70:73] offset:5120
	s_waitcnt vmcnt(12)
	ds_write_b128 v46, v[74:77] offset:6400
	s_waitcnt lgkmcnt(7)
	v_mfma_f32_32x32x16_bf16 v[16:31], v[20:23], v[16:19], 0
	s_waitcnt lgkmcnt(6)
	v_mfma_f32_32x32x16_bf16 v[16:31], v[78:81], v[82:85], v[16:31]
	ds_read_b128 v[78:81], v47 offset:5120
	ds_read_b128 v[82:85], v47
	ds_read_b128 v[86:89], v47 offset:32
	s_waitcnt lgkmcnt(1)
	v_mfma_f32_32x32x16_bf16 v[0:15], v[82:85], v[78:81], v[0:15]
	ds_read_b128 v[82:85], v47 offset:2560
	s_waitcnt lgkmcnt(0)
	v_mfma_f32_32x32x16_bf16 v[16:31], v[82:85], v[78:81], v[16:31]
	ds_read_b128 v[78:81], v47 offset:5152
	ds_read_b128 v[82:85], v47 offset:2592
	s_waitcnt vmcnt(11)
	ds_write_b128 v46, v[102:105]
	s_waitcnt vmcnt(10)
	ds_write_b128 v46, v[106:109] offset:1280
	s_waitcnt vmcnt(9)
	ds_write_b128 v46, v[110:113] offset:2560
	s_waitcnt vmcnt(8)
	ds_write_b128 v46, v[114:117] offset:3840
	s_waitcnt vmcnt(7)
	ds_write_b128 v46, v[118:121] offset:5120
	s_waitcnt vmcnt(6)
	ds_write_b128 v46, v[122:125] offset:6400
	s_waitcnt lgkmcnt(7)
	v_mfma_f32_32x32x16_bf16 v[0:15], v[86:89], v[78:81], v[0:15]
	s_waitcnt lgkmcnt(6)
	v_mfma_f32_32x32x16_bf16 v[16:31], v[82:85], v[78:81], v[16:31]
	ds_read_b128 v[78:81], v47 offset:5120
	ds_read_b128 v[82:85], v47
	ds_read_b128 v[86:89], v47 offset:32
	s_waitcnt lgkmcnt(1)
	v_mfma_f32_32x32x16_bf16 v[0:15], v[82:85], v[78:81], v[0:15]
	ds_read_b128 v[82:85], v47 offset:2560
	s_waitcnt lgkmcnt(0)
	v_mfma_f32_32x32x16_bf16 v[16:31], v[82:85], v[78:81], v[16:31]
	ds_read_b128 v[78:81], v47 offset:5152
	ds_read_b128 v[82:85], v47 offset:2592
	s_waitcnt vmcnt(5)
	ds_write_b128 v46, v[126:129]
	s_waitcnt vmcnt(4)
	ds_write_b128 v46, v[130:133] offset:1280
	s_waitcnt vmcnt(3)
	ds_write_b128 v46, v[134:137] offset:2560
	s_waitcnt vmcnt(2)
	ds_write_b128 v46, v[138:141] offset:3840
	s_waitcnt vmcnt(1)
	ds_write_b128 v46, v[142:145] offset:5120
	s_waitcnt vmcnt(0)
	ds_write_b128 v46, v[146:149] offset:6400
	s_waitcnt lgkmcnt(7)
	v_mfma_f32_32x32x16_bf16 v[0:15], v[86:89], v[78:81], v[0:15]
	ds_read_b128 v[54:57], v47 offset:5120
	ds_read_b128 v[58:61], v47
	ds_read_b128 v[62:65], v47 offset:32
	s_waitcnt lgkmcnt(1)
	v_mfma_f32_32x32x16_bf16 v[0:15], v[58:61], v[54:57], v[0:15]
	ds_read_b128 v[58:61], v47 offset:2560
	v_mfma_f32_32x32x16_bf16 v[16:31], v[82:85], v[78:81], v[16:31]
	s_waitcnt lgkmcnt(0)
	v_mfma_f32_32x32x16_bf16 v[16:31], v[58:61], v[54:57], v[16:31]
	ds_read_b128 v[54:57], v47 offset:5152
	ds_read_b128 v[58:61], v47 offset:2592
	s_waitcnt lgkmcnt(1)
	v_mfma_f32_32x32x16_bf16 v[0:15], v[62:65], v[54:57], v[0:15]
	s_waitcnt lgkmcnt(0)
	v_mfma_f32_32x32x16_bf16 v[16:31], v[58:61], v[54:57], v[16:31]
	s_nop 9
	ds_write2st64_b32 v48, v0, v1 offset1:1
	s_nop 0
	ds_write2st64_b32 v48, v16, v17 offset0:16 offset1:17
	ds_write2st64_b32 v48, v2, v3 offset0:2 offset1:3
	ds_write2st64_b32 v48, v18, v19 offset0:18 offset1:19
	ds_write2st64_b32 v48, v4, v5 offset0:4 offset1:5
	ds_write2st64_b32 v48, v20, v21 offset0:20 offset1:21
	ds_write2st64_b32 v48, v6, v7 offset0:6 offset1:7
	ds_write2st64_b32 v48, v22, v23 offset0:22 offset1:23
	ds_write2st64_b32 v48, v8, v9 offset0:8 offset1:9
	ds_write2st64_b32 v48, v24, v25 offset0:24 offset1:25
	ds_write2st64_b32 v48, v10, v11 offset0:10 offset1:11
	ds_write2st64_b32 v48, v26, v27 offset0:26 offset1:27
	ds_write2st64_b32 v48, v12, v13 offset0:12 offset1:13
	ds_write2st64_b32 v48, v28, v29 offset0:28 offset1:29
	ds_write2st64_b32 v48, v14, v15 offset0:14 offset1:15
	ds_write2st64_b32 v48, v30, v31 offset0:30 offset1:31
	s_waitcnt lgkmcnt(0)
	s_barrier
	ds_read2st64_b32 v[2:3], v49 offset1:32
	v_or_b32_e32 v4, s0, v41
	s_lshl_b32 s0, s15, 1
	v_lshl_add_u64 v[0:1], v[38:39], 0, s[0:1]
	s_cmpk_lt_i32 s11, 0x100
	s_waitcnt lgkmcnt(0)
	v_add_f32_e32 v2, 0, v2
	v_add_f32_e32 v5, v2, v3
	ds_read2st64_b32 v[2:3], v49 offset0:64 offset1:96
	s_waitcnt lgkmcnt(0)
	v_add_f32_e32 v2, v5, v2
	v_add_f32_e32 v5, v2, v3
	ds_read2st64_b32 v[2:3], v49 offset0:128 offset1:160
	s_waitcnt lgkmcnt(0)
	v_add_f32_e32 v2, v5, v2
	v_add_f32_e32 v5, v2, v3
	ds_read2st64_b32 v[2:3], v49 offset0:192 offset1:224
	s_waitcnt lgkmcnt(0)
	v_add_f32_e32 v2, v5, v2
	v_add_f32_e32 v2, v2, v3
	v_cvt_pk_bf16_f32 v5, v2, s0
	v_add_u32_e32 v2, v4, v42
	v_ashrrev_i32_e32 v3, 31, v2
	v_lshlrev_b64 v[2:3], 11, v[2:3]
	v_lshl_add_u64 v[2:3], v[0:1], 0, v[2:3]
	global_store_short v[2:3], v5, off
	ds_read2st64_b32 v[2:3], v50 offset1:32
	s_waitcnt lgkmcnt(0)
	v_add_f32_e32 v2, 0, v2
	v_add_f32_e32 v5, v2, v3
	ds_read2st64_b32 v[2:3], v50 offset0:64 offset1:96
	s_waitcnt lgkmcnt(0)
	v_add_f32_e32 v2, v5, v2
	v_add_f32_e32 v5, v2, v3
	ds_read2st64_b32 v[2:3], v50 offset0:128 offset1:160
	s_waitcnt lgkmcnt(0)
	v_add_f32_e32 v2, v5, v2
	v_add_f32_e32 v5, v2, v3
	ds_read2st64_b32 v[2:3], v50 offset0:192 offset1:224
	s_waitcnt lgkmcnt(0)
	v_add_f32_e32 v2, v5, v2
	v_add_f32_e32 v2, v2, v3
	v_cvt_pk_bf16_f32 v5, v2, s0
	v_add_u32_e32 v2, v4, v43
	v_ashrrev_i32_e32 v3, 31, v2
	v_lshlrev_b64 v[2:3], 11, v[2:3]
	v_lshl_add_u64 v[2:3], v[0:1], 0, v[2:3]
	global_store_short v[2:3], v5, off
	ds_read2st64_b32 v[2:3], v51 offset1:32
	s_waitcnt lgkmcnt(0)
	v_add_f32_e32 v2, 0, v2
	v_add_f32_e32 v5, v2, v3
	ds_read2st64_b32 v[2:3], v51 offset0:64 offset1:96
	s_waitcnt lgkmcnt(0)
	v_add_f32_e32 v2, v5, v2
	v_add_f32_e32 v5, v2, v3
	ds_read2st64_b32 v[2:3], v51 offset0:128 offset1:160
	s_waitcnt lgkmcnt(0)
	v_add_f32_e32 v2, v5, v2
	v_add_f32_e32 v5, v2, v3
	ds_read2st64_b32 v[2:3], v51 offset0:192 offset1:224
	s_waitcnt lgkmcnt(0)
	v_add_f32_e32 v2, v5, v2
	v_add_f32_e32 v2, v2, v3
	v_cvt_pk_bf16_f32 v5, v2, s0
	v_add_u32_e32 v2, v4, v44
	v_ashrrev_i32_e32 v3, 31, v2
	v_lshlrev_b64 v[2:3], 11, v[2:3]
	v_lshl_add_u64 v[2:3], v[0:1], 0, v[2:3]
	global_store_short v[2:3], v5, off
	ds_read2st64_b32 v[2:3], v52 offset1:32
	s_waitcnt lgkmcnt(0)
	v_add_f32_e32 v2, 0, v2
	v_add_f32_e32 v5, v2, v3
	ds_read2st64_b32 v[2:3], v52 offset0:64 offset1:96
	s_waitcnt lgkmcnt(0)
	v_add_f32_e32 v2, v5, v2
	v_add_f32_e32 v5, v2, v3
	ds_read2st64_b32 v[2:3], v52 offset0:128 offset1:160
	s_waitcnt lgkmcnt(0)
	v_add_f32_e32 v2, v5, v2
	v_add_f32_e32 v5, v2, v3
	ds_read2st64_b32 v[2:3], v52 offset0:192 offset1:224
	s_waitcnt lgkmcnt(0)
	v_add_f32_e32 v2, v5, v2
	v_add_f32_e32 v2, v2, v3
	v_cvt_pk_bf16_f32 v5, v2, s0
	v_add_u32_e32 v2, v4, v45
	v_ashrrev_i32_e32 v3, 31, v2
	v_lshlrev_b64 v[2:3], 11, v[2:3]
	v_lshl_add_u64 v[0:1], v[0:1], 0, v[2:3]
	global_store_short v[0:1], v5, off
	s_barrier
	s_cbranch_scc1 .LBB0_933

.LBB0_1109:
	s_and_b32 s0, s5, 0xffffffc0
	v_or_b32_e32 v0, s0, v40
	v_ashrrev_i32_e32 v1, 31, v0
	v_lshlrev_b64 v[0:1], 11, v[0:1]
	v_lshl_add_u64 v[90:91], v[34:35], 0, v[0:1]
	v_add_co_u32_e32 v94, vcc, 0x8000, v90
	s_and_b32 s8, s4, 0x3e0
	s_nop 0
	v_addc_co_u32_e32 v95, vcc, 0, v91, vcc
	v_add_co_u32_e32 v96, vcc, s9, v90
	v_or_b32_e32 v0, s8, v40
	s_nop 0
	v_addc_co_u32_e32 v97, vcc, 0, v91, vcc
	v_lshlrev_b32_e32 v32, 11, v0
	v_add_co_u32_e32 v98, vcc, 0x18000, v90
	v_lshl_add_u64 v[92:93], v[36:37], 0, v[32:33]
	s_nop 0
	v_addc_co_u32_e32 v99, vcc, 0, v91, vcc
	v_add_co_u32_e32 v100, vcc, 0x8000, v92
	global_load_dwordx4 v[0:3], v[90:91], off
	global_load_dwordx4 v[4:7], v[94:95], off
	v_addc_co_u32_e32 v101, vcc, 0, v93, vcc
	global_load_dwordx4 v[8:11], v[96:97], off
	global_load_dwordx4 v[12:15], v[98:99], off
	global_load_dwordx4 v[16:19], v[100:101], off
	global_load_dwordx4 v[20:23], v[92:93], off
	global_load_dwordx4 v[54:57], v[90:91], off offset:64
	global_load_dwordx4 v[58:61], v[94:95], off offset:64
	global_load_dwordx4 v[62:65], v[96:97], off offset:64
	global_load_dwordx4 v[66:69], v[98:99], off offset:64
	global_load_dwordx4 v[70:73], v[92:93], off offset:64
	global_load_dwordx4 v[74:77], v[100:101], off offset:64
	global_load_dwordx4 v[102:105], v[90:91], off offset:128
	global_load_dwordx4 v[106:109], v[94:95], off offset:128
	global_load_dwordx4 v[110:113], v[96:97], off offset:128
	global_load_dwordx4 v[114:117], v[98:99], off offset:128
	global_load_dwordx4 v[118:121], v[92:93], off offset:128
	global_load_dwordx4 v[122:125], v[100:101], off offset:128
	global_load_dwordx4 v[126:129], v[90:91], off offset:192
	global_load_dwordx4 v[130:133], v[94:95], off offset:192
	global_load_dwordx4 v[134:137], v[96:97], off offset:192
	global_load_dwordx4 v[138:141], v[98:99], off offset:192
	global_load_dwordx4 v[142:145], v[92:93], off offset:192
	global_load_dwordx4 v[146:149], v[100:101], off offset:192
	s_add_i32 s7, s7, s96
	s_add_i32 s4, s4, s86
	s_add_i32 s5, s5, s6
	s_waitcnt vmcnt(23)
	ds_write_b128 v46, v[0:3]
	s_waitcnt vmcnt(22)
	ds_write_b128 v46, v[4:7] offset:1280
	s_waitcnt vmcnt(21)
	ds_write_b128 v46, v[8:11] offset:2560
	s_waitcnt vmcnt(20)
	ds_write_b128 v46, v[12:15] offset:3840
	s_waitcnt vmcnt(18)
	ds_write_b128 v46, v[20:23] offset:5120
	ds_write_b128 v46, v[16:19] offset:6400
	ds_read_b128 v[16:19], v47 offset:5120
	ds_read_b128 v[0:3], v47
	ds_read_b128 v[78:81], v47 offset:32
	s_waitcnt lgkmcnt(1)
	v_mfma_f32_32x32x16_bf16 v[0:15], v[0:3], v[16:19], 0
	ds_read_b128 v[82:85], v47 offset:5152
	ds_read_b128 v[20:23], v47 offset:2560
	s_waitcnt lgkmcnt(1)
	v_mfma_f32_32x32x16_bf16 v[0:15], v[78:81], v[82:85], v[0:15]
	ds_read_b128 v[78:81], v47 offset:2592
	s_waitcnt vmcnt(17)
	ds_write_b128 v46, v[54:57]
	s_waitcnt vmcnt(16)
	ds_write_b128 v46, v[58:61] offset:1280
	s_waitcnt vmcnt(15)
	ds_write_b128 v46, v[62:65] offset:2560
	s_waitcnt vmcnt(14)
	ds_write_b128 v46, v[66:69] offset:3840
	s_waitcnt vmcnt(13)
	ds_write_b128 v46, v[70:73] offset:5120
	s_waitcnt vmcnt(12)
	ds_write_b128 v46, v[74:77] offset:6400
	s_waitcnt lgkmcnt(7)
	v_mfma_f32_32x32x16_bf16 v[16:31], v[20:23], v[16:19], 0
	s_waitcnt lgkmcnt(6)
	v_mfma_f32_32x32x16_bf16 v[16:31], v[78:81], v[82:85], v[16:31]
	ds_read_b128 v[78:81], v47 offset:5120
	ds_read_b128 v[82:85], v47
	ds_read_b128 v[86:89], v47 offset:32
	s_waitcnt lgkmcnt(1)
	v_mfma_f32_32x32x16_bf16 v[0:15], v[82:85], v[78:81], v[0:15]
	ds_read_b128 v[82:85], v47 offset:2560
	s_waitcnt lgkmcnt(0)
	v_mfma_f32_32x32x16_bf16 v[16:31], v[82:85], v[78:81], v[16:31]
	ds_read_b128 v[78:81], v47 offset:5152
	ds_read_b128 v[82:85], v47 offset:2592
	s_waitcnt vmcnt(11)
	ds_write_b128 v46, v[102:105]
	s_waitcnt vmcnt(10)
	ds_write_b128 v46, v[106:109] offset:1280
	s_waitcnt vmcnt(9)
	ds_write_b128 v46, v[110:113] offset:2560
	s_waitcnt vmcnt(8)
	ds_write_b128 v46, v[114:117] offset:3840
	s_waitcnt vmcnt(7)
	ds_write_b128 v46, v[118:121] offset:5120
	s_waitcnt vmcnt(6)
	ds_write_b128 v46, v[122:125] offset:6400
	s_waitcnt lgkmcnt(7)
	v_mfma_f32_32x32x16_bf16 v[0:15], v[86:89], v[78:81], v[0:15]
	s_waitcnt lgkmcnt(6)
	v_mfma_f32_32x32x16_bf16 v[16:31], v[82:85], v[78:81], v[16:31]
	ds_read_b128 v[78:81], v47 offset:5120
	ds_read_b128 v[82:85], v47
	ds_read_b128 v[86:89], v47 offset:32
	s_waitcnt lgkmcnt(1)
	v_mfma_f32_32x32x16_bf16 v[0:15], v[82:85], v[78:81], v[0:15]
	ds_read_b128 v[82:85], v47 offset:2560
	s_waitcnt lgkmcnt(0)
	v_mfma_f32_32x32x16_bf16 v[16:31], v[82:85], v[78:81], v[16:31]
	ds_read_b128 v[78:81], v47 offset:5152
	ds_read_b128 v[82:85], v47 offset:2592
	s_waitcnt vmcnt(5)
	ds_write_b128 v46, v[126:129]
	s_waitcnt vmcnt(4)
	ds_write_b128 v46, v[130:133] offset:1280
	s_waitcnt vmcnt(3)
	ds_write_b128 v46, v[134:137] offset:2560
	s_waitcnt vmcnt(2)
	ds_write_b128 v46, v[138:141] offset:3840
	s_waitcnt vmcnt(1)
	ds_write_b128 v46, v[142:145] offset:5120
	s_waitcnt vmcnt(0)
	ds_write_b128 v46, v[146:149] offset:6400
	s_waitcnt lgkmcnt(7)
	v_mfma_f32_32x32x16_bf16 v[0:15], v[86:89], v[78:81], v[0:15]
	ds_read_b128 v[54:57], v47 offset:5120
	ds_read_b128 v[58:61], v47
	ds_read_b128 v[62:65], v47 offset:32
	s_waitcnt lgkmcnt(1)
	v_mfma_f32_32x32x16_bf16 v[0:15], v[58:61], v[54:57], v[0:15]
	ds_read_b128 v[58:61], v47 offset:2560
	v_mfma_f32_32x32x16_bf16 v[16:31], v[82:85], v[78:81], v[16:31]
	s_waitcnt lgkmcnt(0)
	v_mfma_f32_32x32x16_bf16 v[16:31], v[58:61], v[54:57], v[16:31]
	ds_read_b128 v[54:57], v47 offset:5152
	ds_read_b128 v[58:61], v47 offset:2592
	s_waitcnt lgkmcnt(1)
	v_mfma_f32_32x32x16_bf16 v[0:15], v[62:65], v[54:57], v[0:15]
	s_waitcnt lgkmcnt(0)
	v_mfma_f32_32x32x16_bf16 v[16:31], v[58:61], v[54:57], v[16:31]
	s_nop 9
	ds_write2st64_b32 v48, v0, v1 offset1:1
	s_nop 0
	ds_write2st64_b32 v48, v16, v17 offset0:16 offset1:17
	ds_write2st64_b32 v48, v2, v3 offset0:2 offset1:3
	ds_write2st64_b32 v48, v18, v19 offset0:18 offset1:19
	ds_write2st64_b32 v48, v4, v5 offset0:4 offset1:5
	ds_write2st64_b32 v48, v20, v21 offset0:20 offset1:21
	ds_write2st64_b32 v48, v6, v7 offset0:6 offset1:7
	ds_write2st64_b32 v48, v22, v23 offset0:22 offset1:23
	ds_write2st64_b32 v48, v8, v9 offset0:8 offset1:9
	ds_write2st64_b32 v48, v24, v25 offset0:24 offset1:25
	ds_write2st64_b32 v48, v10, v11 offset0:10 offset1:11
	ds_write2st64_b32 v48, v26, v27 offset0:26 offset1:27
	ds_write2st64_b32 v48, v12, v13 offset0:12 offset1:13
	ds_write2st64_b32 v48, v28, v29 offset0:28 offset1:29
	ds_write2st64_b32 v48, v14, v15 offset0:14 offset1:15
	ds_write2st64_b32 v48, v30, v31 offset0:30 offset1:31
	s_waitcnt lgkmcnt(0)
	s_barrier
	ds_read2st64_b32 v[2:3], v49 offset1:32
	v_or_b32_e32 v4, s0, v41
	s_lshl_b32 s0, s8, 1
	v_lshl_add_u64 v[0:1], v[38:39], 0, s[0:1]
	s_cmpk_lt_i32 s7, 0x100
	s_waitcnt lgkmcnt(0)
	v_add_f32_e32 v2, 0, v2
	v_add_f32_e32 v5, v2, v3
	ds_read2st64_b32 v[2:3], v49 offset0:64 offset1:96
	s_waitcnt lgkmcnt(0)
	v_add_f32_e32 v2, v5, v2
	v_add_f32_e32 v5, v2, v3
	ds_read2st64_b32 v[2:3], v49 offset0:128 offset1:160
	s_waitcnt lgkmcnt(0)
	v_add_f32_e32 v2, v5, v2
	v_add_f32_e32 v5, v2, v3
	ds_read2st64_b32 v[2:3], v49 offset0:192 offset1:224
	s_waitcnt lgkmcnt(0)
	v_add_f32_e32 v2, v5, v2
	v_add_f32_e32 v2, v2, v3
	v_mul_f32_e32 v2, 0x3db8aa3b, v2
	v_cvt_pk_bf16_f32 v5, v2, s0
	v_add_u32_e32 v2, v4, v42
	v_ashrrev_i32_e32 v3, 31, v2
	v_lshlrev_b64 v[2:3], 11, v[2:3]
	v_lshl_add_u64 v[2:3], v[0:1], 0, v[2:3]
	global_store_short v[2:3], v5, off
	ds_read2st64_b32 v[2:3], v50 offset1:32
	s_waitcnt lgkmcnt(0)
	v_add_f32_e32 v2, 0, v2
	v_add_f32_e32 v5, v2, v3
	ds_read2st64_b32 v[2:3], v50 offset0:64 offset1:96
	s_waitcnt lgkmcnt(0)
	v_add_f32_e32 v2, v5, v2
	v_add_f32_e32 v5, v2, v3
	ds_read2st64_b32 v[2:3], v50 offset0:128 offset1:160
	s_waitcnt lgkmcnt(0)
	v_add_f32_e32 v2, v5, v2
	v_add_f32_e32 v5, v2, v3
	ds_read2st64_b32 v[2:3], v50 offset0:192 offset1:224
	s_waitcnt lgkmcnt(0)
	v_add_f32_e32 v2, v5, v2
	v_add_f32_e32 v2, v2, v3
	v_mul_f32_e32 v2, 0x3db8aa3b, v2
	v_cvt_pk_bf16_f32 v5, v2, s0
	v_add_u32_e32 v2, v4, v43
	v_ashrrev_i32_e32 v3, 31, v2
	v_lshlrev_b64 v[2:3], 11, v[2:3]
	v_lshl_add_u64 v[2:3], v[0:1], 0, v[2:3]
	global_store_short v[2:3], v5, off
	ds_read2st64_b32 v[2:3], v51 offset1:32
	s_waitcnt lgkmcnt(0)
	v_add_f32_e32 v2, 0, v2
	v_add_f32_e32 v5, v2, v3
	ds_read2st64_b32 v[2:3], v51 offset0:64 offset1:96
	s_waitcnt lgkmcnt(0)
	v_add_f32_e32 v2, v5, v2
	v_add_f32_e32 v5, v2, v3
	ds_read2st64_b32 v[2:3], v51 offset0:128 offset1:160
	s_waitcnt lgkmcnt(0)
	v_add_f32_e32 v2, v5, v2
	v_add_f32_e32 v5, v2, v3
	ds_read2st64_b32 v[2:3], v51 offset0:192 offset1:224
	s_waitcnt lgkmcnt(0)
	v_add_f32_e32 v2, v5, v2
	v_add_f32_e32 v2, v2, v3
	v_mul_f32_e32 v2, 0x3db8aa3b, v2
	v_cvt_pk_bf16_f32 v5, v2, s0
	v_add_u32_e32 v2, v4, v44
	v_ashrrev_i32_e32 v3, 31, v2
	v_lshlrev_b64 v[2:3], 11, v[2:3]
	v_lshl_add_u64 v[2:3], v[0:1], 0, v[2:3]
	global_store_short v[2:3], v5, off
	ds_read2st64_b32 v[2:3], v52 offset1:32
	s_waitcnt lgkmcnt(0)
	v_add_f32_e32 v2, 0, v2
	v_add_f32_e32 v5, v2, v3
	ds_read2st64_b32 v[2:3], v52 offset0:64 offset1:96
	s_waitcnt lgkmcnt(0)
	v_add_f32_e32 v2, v5, v2
	v_add_f32_e32 v5, v2, v3
	ds_read2st64_b32 v[2:3], v52 offset0:128 offset1:160
	s_waitcnt lgkmcnt(0)
	v_add_f32_e32 v2, v5, v2
	v_add_f32_e32 v5, v2, v3
	ds_read2st64_b32 v[2:3], v52 offset0:192 offset1:224
	s_waitcnt lgkmcnt(0)
	v_add_f32_e32 v2, v5, v2
	v_add_f32_e32 v2, v2, v3
	v_mul_f32_e32 v2, 0x3db8aa3b, v2
	v_cvt_pk_bf16_f32 v5, v2, s0
	v_add_u32_e32 v2, v4, v45
	v_ashrrev_i32_e32 v3, 31, v2
	v_lshlrev_b64 v[2:3], 11, v[2:3]
	v_lshl_add_u64 v[0:1], v[0:1], 0, v[2:3]
	global_store_short v[0:1], v5, off
	s_barrier
	s_cbranch_scc1 .LBB0_1109

.LBB0_1243:
	s_and_b32 s0, s5, 0xffffffc0
	v_or_b32_e32 v0, s0, v40
	v_ashrrev_i32_e32 v1, 31, v0
	v_lshlrev_b64 v[0:1], 11, v[0:1]
	v_lshl_add_u64 v[90:91], v[34:35], 0, v[0:1]
	v_add_co_u32_e32 v94, vcc, 0x8000, v90
	s_and_b32 s8, s4, 0x3e0
	s_nop 0
	v_addc_co_u32_e32 v95, vcc, 0, v91, vcc
	v_add_co_u32_e32 v96, vcc, s9, v90
	v_or_b32_e32 v0, s8, v40
	s_nop 0
	v_addc_co_u32_e32 v97, vcc, 0, v91, vcc
	v_lshlrev_b32_e32 v32, 11, v0
	v_add_co_u32_e32 v98, vcc, 0x18000, v90
	v_lshl_add_u64 v[92:93], v[36:37], 0, v[32:33]
	s_nop 0
	v_addc_co_u32_e32 v99, vcc, 0, v91, vcc
	v_add_co_u32_e32 v100, vcc, 0x8000, v92
	global_load_dwordx4 v[0:3], v[90:91], off
	global_load_dwordx4 v[4:7], v[94:95], off
	v_addc_co_u32_e32 v101, vcc, 0, v93, vcc
	global_load_dwordx4 v[8:11], v[96:97], off
	global_load_dwordx4 v[12:15], v[98:99], off
	global_load_dwordx4 v[16:19], v[100:101], off
	global_load_dwordx4 v[20:23], v[92:93], off
	global_load_dwordx4 v[54:57], v[90:91], off offset:64
	global_load_dwordx4 v[58:61], v[94:95], off offset:64
	global_load_dwordx4 v[62:65], v[96:97], off offset:64
	global_load_dwordx4 v[66:69], v[98:99], off offset:64
	global_load_dwordx4 v[70:73], v[92:93], off offset:64
	global_load_dwordx4 v[74:77], v[100:101], off offset:64
	global_load_dwordx4 v[102:105], v[90:91], off offset:128
	global_load_dwordx4 v[106:109], v[94:95], off offset:128
	global_load_dwordx4 v[110:113], v[96:97], off offset:128
	global_load_dwordx4 v[114:117], v[98:99], off offset:128
	global_load_dwordx4 v[118:121], v[92:93], off offset:128
	global_load_dwordx4 v[122:125], v[100:101], off offset:128
	global_load_dwordx4 v[126:129], v[90:91], off offset:192
	global_load_dwordx4 v[130:133], v[94:95], off offset:192
	global_load_dwordx4 v[134:137], v[96:97], off offset:192
	global_load_dwordx4 v[138:141], v[98:99], off offset:192
	global_load_dwordx4 v[142:145], v[92:93], off offset:192
	global_load_dwordx4 v[146:149], v[100:101], off offset:192
	s_add_i32 s7, s7, s96
	s_add_i32 s4, s4, s86
	s_add_i32 s5, s5, s6
	s_waitcnt vmcnt(18)
	ds_write_b128 v46, v[0:3]
	ds_write_b128 v46, v[4:7] offset:1280
	ds_write_b128 v46, v[8:11] offset:2560
	ds_write_b128 v46, v[12:15] offset:3840
	ds_write_b128 v46, v[20:23] offset:5120
	ds_write_b128 v46, v[16:19] offset:6400
	ds_read_b128 v[16:19], v47 offset:5120
	ds_read_b128 v[0:3], v47
	ds_read_b128 v[78:81], v47 offset:32
	s_waitcnt lgkmcnt(1)
	v_mfma_f32_32x32x16_bf16 v[0:15], v[0:3], v[16:19], 0
	ds_read_b128 v[82:85], v47 offset:5152
	ds_read_b128 v[20:23], v47 offset:2560
	s_waitcnt lgkmcnt(1)
	v_mfma_f32_32x32x16_bf16 v[0:15], v[78:81], v[82:85], v[0:15]
	ds_read_b128 v[78:81], v47 offset:2592
	s_waitcnt vmcnt(17)
	ds_write_b128 v46, v[54:57]
	s_waitcnt vmcnt(16)
	ds_write_b128 v46, v[58:61] offset:1280
	s_waitcnt vmcnt(15)
	ds_write_b128 v46, v[62:65] offset:2560
	s_waitcnt vmcnt(14)
	ds_write_b128 v46, v[66:69] offset:3840
	s_waitcnt vmcnt(13)
	ds_write_b128 v46, v[70:73] offset:5120
	s_waitcnt vmcnt(12)
	ds_write_b128 v46, v[74:77] offset:6400
	s_waitcnt lgkmcnt(7)
	v_mfma_f32_32x32x16_bf16 v[16:31], v[20:23], v[16:19], 0
	s_waitcnt lgkmcnt(6)
	v_mfma_f32_32x32x16_bf16 v[16:31], v[78:81], v[82:85], v[16:31]
	ds_read_b128 v[78:81], v47 offset:5120
	ds_read_b128 v[82:85], v47
	ds_read_b128 v[86:89], v47 offset:32
	s_waitcnt lgkmcnt(1)
	v_mfma_f32_32x32x16_bf16 v[0:15], v[82:85], v[78:81], v[0:15]
	ds_read_b128 v[82:85], v47 offset:2560
	s_waitcnt lgkmcnt(0)
	v_mfma_f32_32x32x16_bf16 v[16:31], v[82:85], v[78:81], v[16:31]
	ds_read_b128 v[78:81], v47 offset:5152
	ds_read_b128 v[82:85], v47 offset:2592
	s_waitcnt vmcnt(11)
	ds_write_b128 v46, v[102:105]
	s_waitcnt vmcnt(10)
	ds_write_b128 v46, v[106:109] offset:1280
	s_waitcnt vmcnt(9)
	ds_write_b128 v46, v[110:113] offset:2560
	s_waitcnt vmcnt(8)
	ds_write_b128 v46, v[114:117] offset:3840
	s_waitcnt vmcnt(7)
	ds_write_b128 v46, v[118:121] offset:5120
	s_waitcnt vmcnt(6)
	ds_write_b128 v46, v[122:125] offset:6400
	s_waitcnt lgkmcnt(7)
	v_mfma_f32_32x32x16_bf16 v[0:15], v[86:89], v[78:81], v[0:15]
	s_waitcnt lgkmcnt(6)
	v_mfma_f32_32x32x16_bf16 v[16:31], v[82:85], v[78:81], v[16:31]
	ds_read_b128 v[78:81], v47 offset:5120
	ds_read_b128 v[82:85], v47
	ds_read_b128 v[86:89], v47 offset:32
	s_waitcnt lgkmcnt(1)
	v_mfma_f32_32x32x16_bf16 v[0:15], v[82:85], v[78:81], v[0:15]
	ds_read_b128 v[82:85], v47 offset:2560
	s_waitcnt lgkmcnt(0)
	v_mfma_f32_32x32x16_bf16 v[16:31], v[82:85], v[78:81], v[16:31]
	ds_read_b128 v[78:81], v47 offset:5152
	ds_read_b128 v[82:85], v47 offset:2592
	s_waitcnt vmcnt(5)
	ds_write_b128 v46, v[126:129]
	s_waitcnt vmcnt(4)
	ds_write_b128 v46, v[130:133] offset:1280
	s_waitcnt vmcnt(3)
	ds_write_b128 v46, v[134:137] offset:2560
	s_waitcnt vmcnt(2)
	ds_write_b128 v46, v[138:141] offset:3840
	s_waitcnt vmcnt(1)
	ds_write_b128 v46, v[142:145] offset:5120
	s_waitcnt vmcnt(0)
	ds_write_b128 v46, v[146:149] offset:6400
	s_waitcnt lgkmcnt(7)
	v_mfma_f32_32x32x16_bf16 v[0:15], v[86:89], v[78:81], v[0:15]
	ds_read_b128 v[54:57], v47 offset:5120
	ds_read_b128 v[58:61], v47
	ds_read_b128 v[62:65], v47 offset:32
	s_waitcnt lgkmcnt(1)
	v_mfma_f32_32x32x16_bf16 v[0:15], v[58:61], v[54:57], v[0:15]
	ds_read_b128 v[58:61], v47 offset:2560
	v_mfma_f32_32x32x16_bf16 v[16:31], v[82:85], v[78:81], v[16:31]
	s_waitcnt lgkmcnt(0)
	v_mfma_f32_32x32x16_bf16 v[16:31], v[58:61], v[54:57], v[16:31]
	ds_read_b128 v[54:57], v47 offset:5152
	ds_read_b128 v[58:61], v47 offset:2592
	s_waitcnt lgkmcnt(1)
	v_mfma_f32_32x32x16_bf16 v[0:15], v[62:65], v[54:57], v[0:15]
	s_waitcnt lgkmcnt(0)
	v_mfma_f32_32x32x16_bf16 v[16:31], v[58:61], v[54:57], v[16:31]
	s_nop 9
	ds_write2st64_b32 v48, v0, v1 offset1:1
	s_nop 0
	ds_write2st64_b32 v48, v16, v17 offset0:16 offset1:17
	ds_write2st64_b32 v48, v2, v3 offset0:2 offset1:3
	ds_write2st64_b32 v48, v18, v19 offset0:18 offset1:19
	ds_write2st64_b32 v48, v4, v5 offset0:4 offset1:5
	ds_write2st64_b32 v48, v20, v21 offset0:20 offset1:21
	ds_write2st64_b32 v48, v6, v7 offset0:6 offset1:7
	ds_write2st64_b32 v48, v22, v23 offset0:22 offset1:23
	ds_write2st64_b32 v48, v8, v9 offset0:8 offset1:9
	ds_write2st64_b32 v48, v24, v25 offset0:24 offset1:25
	ds_write2st64_b32 v48, v10, v11 offset0:10 offset1:11
	ds_write2st64_b32 v48, v26, v27 offset0:26 offset1:27
	ds_write2st64_b32 v48, v12, v13 offset0:12 offset1:13
	ds_write2st64_b32 v48, v28, v29 offset0:28 offset1:29
	ds_write2st64_b32 v48, v14, v15 offset0:14 offset1:15
	ds_write2st64_b32 v48, v30, v31 offset0:30 offset1:31
	s_waitcnt lgkmcnt(0)
	s_barrier
	ds_read2st64_b32 v[2:3], v49 offset1:32
	v_or_b32_e32 v4, s0, v41
	s_lshl_b32 s0, s8, 1
	v_lshl_add_u64 v[0:1], v[38:39], 0, s[0:1]
	s_cmpk_lt_i32 s7, 0x100
	s_waitcnt lgkmcnt(0)
	v_add_f32_e32 v2, 0, v2
	v_add_f32_e32 v5, v2, v3
	ds_read2st64_b32 v[2:3], v49 offset0:64 offset1:96
	s_waitcnt lgkmcnt(0)
	v_add_f32_e32 v2, v5, v2
	v_add_f32_e32 v5, v2, v3
	ds_read2st64_b32 v[2:3], v49 offset0:128 offset1:160
	s_waitcnt lgkmcnt(0)
	v_add_f32_e32 v2, v5, v2
	v_add_f32_e32 v5, v2, v3
	ds_read2st64_b32 v[2:3], v49 offset0:192 offset1:224
	s_waitcnt lgkmcnt(0)
	v_add_f32_e32 v2, v5, v2
	v_add_f32_e32 v2, v2, v3
	v_cvt_pk_bf16_f32 v5, v2, s0
	v_add_u32_e32 v2, v4, v42
	v_ashrrev_i32_e32 v3, 31, v2
	v_lshlrev_b64 v[2:3], 11, v[2:3]
	v_lshl_add_u64 v[2:3], v[0:1], 0, v[2:3]
	global_store_short v[2:3], v5, off
	ds_read2st64_b32 v[2:3], v50 offset1:32
	s_waitcnt lgkmcnt(0)
	v_add_f32_e32 v2, 0, v2
	v_add_f32_e32 v5, v2, v3
	ds_read2st64_b32 v[2:3], v50 offset0:64 offset1:96
	s_waitcnt lgkmcnt(0)
	v_add_f32_e32 v2, v5, v2
	v_add_f32_e32 v5, v2, v3
	ds_read2st64_b32 v[2:3], v50 offset0:128 offset1:160
	s_waitcnt lgkmcnt(0)
	v_add_f32_e32 v2, v5, v2
	v_add_f32_e32 v5, v2, v3
	ds_read2st64_b32 v[2:3], v50 offset0:192 offset1:224
	s_waitcnt lgkmcnt(0)
	v_add_f32_e32 v2, v5, v2
	v_add_f32_e32 v2, v2, v3
	v_cvt_pk_bf16_f32 v5, v2, s0
	v_add_u32_e32 v2, v4, v43
	v_ashrrev_i32_e32 v3, 31, v2
	v_lshlrev_b64 v[2:3], 11, v[2:3]
	v_lshl_add_u64 v[2:3], v[0:1], 0, v[2:3]
	global_store_short v[2:3], v5, off
	ds_read2st64_b32 v[2:3], v51 offset1:32
	s_waitcnt lgkmcnt(0)
	v_add_f32_e32 v2, 0, v2
	v_add_f32_e32 v5, v2, v3
	ds_read2st64_b32 v[2:3], v51 offset0:64 offset1:96
	s_waitcnt lgkmcnt(0)
	v_add_f32_e32 v2, v5, v2
	v_add_f32_e32 v5, v2, v3
	ds_read2st64_b32 v[2:3], v51 offset0:128 offset1:160
	s_waitcnt lgkmcnt(0)
	v_add_f32_e32 v2, v5, v2
	v_add_f32_e32 v5, v2, v3
	ds_read2st64_b32 v[2:3], v51 offset0:192 offset1:224
	s_waitcnt lgkmcnt(0)
	v_add_f32_e32 v2, v5, v2
	v_add_f32_e32 v2, v2, v3
	v_cvt_pk_bf16_f32 v5, v2, s0
	v_add_u32_e32 v2, v4, v44
	v_ashrrev_i32_e32 v3, 31, v2
	v_lshlrev_b64 v[2:3], 11, v[2:3]
	v_lshl_add_u64 v[2:3], v[0:1], 0, v[2:3]
	global_store_short v[2:3], v5, off
	ds_read2st64_b32 v[2:3], v52 offset1:32
	s_waitcnt lgkmcnt(0)
	v_add_f32_e32 v2, 0, v2
	v_add_f32_e32 v5, v2, v3
	ds_read2st64_b32 v[2:3], v52 offset0:64 offset1:96
	s_waitcnt lgkmcnt(0)
	v_add_f32_e32 v2, v5, v2
	v_add_f32_e32 v5, v2, v3
	ds_read2st64_b32 v[2:3], v52 offset0:128 offset1:160
	s_waitcnt lgkmcnt(0)
	v_add_f32_e32 v2, v5, v2
	v_add_f32_e32 v5, v2, v3
	ds_read2st64_b32 v[2:3], v52 offset0:192 offset1:224
	s_waitcnt lgkmcnt(0)
	v_add_f32_e32 v2, v5, v2
	v_add_f32_e32 v2, v2, v3
	v_cvt_pk_bf16_f32 v5, v2, s0
	v_add_u32_e32 v2, v4, v45
	v_ashrrev_i32_e32 v3, 31, v2
	v_lshlrev_b64 v[2:3], 11, v[2:3]
	v_lshl_add_u64 v[0:1], v[0:1], 0, v[2:3]
	global_store_short v[0:1], v5, off
	s_barrier
	s_cbranch_scc1 .LBB0_1243
